# P1/P5 GEMM epilogues: the 8 row-statistics (ssq) loads per tile issued together instead of one per vmcnt(0)
# speedup vs baseline: 1.0148x; 1.0148x over previous
.LBB0_180:
	s_mov_b32 s6, s77
	s_lshl_b32 s57, s58, 8
	s_add_i32 s57, s57, s83
	v_or_b32_e32 v172, s57, v143
	v_add_u32_e32 v130, s42, v172
	v_ashrrev_i32_e32 v131, 31, v130
	v_lshlrev_b64 v[132:133], 6, v[130:131]
	v_lshl_add_u64 v[132:133], v[146:147], 0, v[132:133]
	global_load_dwordx4 v[194:197], v[132:133], off
	global_load_dwordx4 v[202:205], v[132:133], off offset:1024
	global_load_dwordx4 v[206:209], v[132:133], off offset:2048
	global_load_dwordx4 v[214:217], v[132:133], off offset:3072
	s_mov_b64 s[100:101], 0x2000
	v_lshl_add_u64 v[246:247], v[132:133], 0, s[100:101]
	global_load_dwordx4 v[218:221], v[246:247], off
	global_load_dwordx4 v[224:227], v[246:247], off offset:1024
	global_load_dwordx4 v[228:231], v[246:247], off offset:2048
	global_load_dwordx4 v[232:235], v[246:247], off offset:3072
	s_mov_b64 s[6:7], -1
	s_cmp_lt_i32 s25, 19
	s_waitcnt vmcnt(6)
	v_add_f32_e32 v131, v196, v197
	v_add_f32_e32 v133, v204, v205
	v_add_f32_e32 v0, v194, v195
	v_add_f32_e32 v130, v202, v203
	v_add_f32_e32 v0, v0, v131
	v_add_f32_e32 v130, v130, v133
	ds_swizzle_b32 v131, v0 offset:swizzle(SWAP,16)
	ds_swizzle_b32 v133, v130 offset:swizzle(SWAP,16)
	s_waitcnt lgkmcnt(0)
	v_add_f32_e32 v0, v0, v131
	v_add_f32_e32 v130, v130, v133
	v_mov_b32_e32 v131, v0
	v_mov_b32_e32 v133, v130
	s_nop 1
	v_permlane32_swap_b32_e32 v0, v131
	v_permlane32_swap_b32_e32 v130, v133
	v_add_f32_e32 v0, v0, v131
	v_add_f32_e32 v130, v130, v133
	v_fmamk_f32 v0, v0, 0x3a800000, v241
	v_fmamk_f32 v130, v130, 0x3a800000, v241
	v_rsq_f32_e32 v156, v0
	v_rsq_f32_e32 v158, v130
	s_waitcnt vmcnt(4)
	v_add_f32_e32 v131, v208, v209
	v_add_f32_e32 v133, v216, v217
	v_add_f32_e32 v0, v206, v207
	v_add_f32_e32 v130, v214, v215
	v_add_f32_e32 v0, v0, v131
	v_add_f32_e32 v130, v130, v133
	ds_swizzle_b32 v131, v0 offset:swizzle(SWAP,16)
	ds_swizzle_b32 v133, v130 offset:swizzle(SWAP,16)
	s_waitcnt lgkmcnt(0)
	v_add_f32_e32 v0, v0, v131
	v_add_f32_e32 v130, v130, v133
	v_mov_b32_e32 v131, v0
	v_mov_b32_e32 v133, v130
	s_nop 1
	v_permlane32_swap_b32_e32 v0, v131
	v_permlane32_swap_b32_e32 v130, v133
	v_add_f32_e32 v0, v0, v131
	v_add_f32_e32 v130, v130, v133
	v_fmamk_f32 v0, v0, 0x3a800000, v241
	v_fmamk_f32 v130, v130, 0x3a800000, v241
	v_rsq_f32_e32 v160, v0
	v_rsq_f32_e32 v162, v130
	s_waitcnt vmcnt(2)
	v_add_f32_e32 v131, v220, v221
	v_add_f32_e32 v133, v226, v227
	v_add_f32_e32 v0, v218, v219
	v_add_f32_e32 v130, v224, v225
	v_add_f32_e32 v0, v0, v131
	v_add_f32_e32 v130, v130, v133
	ds_swizzle_b32 v131, v0 offset:swizzle(SWAP,16)
	ds_swizzle_b32 v133, v130 offset:swizzle(SWAP,16)
	s_waitcnt lgkmcnt(0)
	v_add_f32_e32 v0, v0, v131
	v_add_f32_e32 v130, v130, v133
	v_mov_b32_e32 v131, v0
	v_mov_b32_e32 v133, v130
	s_nop 1
	v_permlane32_swap_b32_e32 v0, v131
	v_permlane32_swap_b32_e32 v130, v133
	v_add_f32_e32 v0, v0, v131
	v_add_f32_e32 v130, v130, v133
	v_fmamk_f32 v0, v0, 0x3a800000, v241
	v_fmamk_f32 v130, v130, 0x3a800000, v241
	v_rsq_f32_e32 v164, v0
	v_rsq_f32_e32 v166, v130
	s_waitcnt vmcnt(0)
	v_add_f32_e32 v131, v230, v231
	v_add_f32_e32 v133, v234, v235
	v_add_f32_e32 v0, v228, v229
	v_add_f32_e32 v130, v232, v233
	v_add_f32_e32 v0, v0, v131
	v_add_f32_e32 v130, v130, v133
	ds_swizzle_b32 v131, v0 offset:swizzle(SWAP,16)
	ds_swizzle_b32 v133, v130 offset:swizzle(SWAP,16)
	s_waitcnt lgkmcnt(0)
	v_add_f32_e32 v0, v0, v131
	v_add_f32_e32 v130, v130, v133
	v_mov_b32_e32 v131, v0
	v_mov_b32_e32 v133, v130
	s_nop 1
	v_permlane32_swap_b32_e32 v0, v131
	v_permlane32_swap_b32_e32 v130, v133
	v_add_f32_e32 v0, v0, v131
	v_add_f32_e32 v130, v130, v133
	v_fmamk_f32 v0, v0, 0x3a800000, v241
	v_fmamk_f32 v130, v130, 0x3a800000, v241
	v_rsq_f32_e32 v168, v0
	v_rsq_f32_e32 v170, v130
	s_nop 0
	s_cbranch_scc0 .LBB0_195
	s_mov_b64 s[34:35], -1
	s_mov_b64 s[6:7], 0
	s_cmp_lt_i32 s25, 13
	s_mov_b64 s[64:65], 0
	s_mov_b64 s[92:93], 0
	s_mov_b64 s[94:95], 0
	s_cbranch_scc1 .LBB0_201
	s_mov_b64 s[80:81], -1
	s_cmp_gt_i32 s25, 15
	s_cbranch_scc0 .LBB0_190
	s_mov_b64 s[80:81], 0
	s_mov_b64 s[64:65], -1
	s_cmp_gt_i32 s25, 16
	s_cbranch_scc0 .LBB0_190
	s_cmp_gt_i32 s25, 17
	s_cbranch_scc0 .LBB0_188
	s_mov_b64 s[64:65], exec
	v_readlane_b32 s34, v255, 0
	v_readlane_b32 s35, v255, 1
	s_and_b64 s[34:35], s[64:65], s[34:35]
	s_mov_b64 exec, s[34:35]
	s_cbranch_execz .LBB0_187
	v_ashrrev_i32_e32 v173, 31, v172
	v_or_b32_e32 v176, 16, v172
	v_pk_mul_f32 v[132:133], v[128:129], v[156:157] op_sel_hi:[1,0]
	v_pk_mul_f32 v[130:131], v[126:127], v[156:157] op_sel_hi:[1,0]
	v_lshl_add_u64 v[174:175], v[172:173], 4, s[18:19]
	v_ashrrev_i32_e32 v177, 31, v176
	global_store_dwordx4 v[174:175], v[130:133], off
	v_lshl_add_u64 v[176:177], v[176:177], 4, s[18:19]
	s_nop 0
	v_pk_mul_f32 v[132:133], v[112:113], v[158:159] op_sel_hi:[1,0]
	v_pk_mul_f32 v[130:131], v[110:111], v[158:159] op_sel_hi:[1,0]
	global_store_dwordx4 v[176:177], v[130:133], off
	v_or_b32_e32 v176, 32, v172
	v_ashrrev_i32_e32 v177, 31, v176
	v_pk_mul_f32 v[132:133], v[96:97], v[160:161] op_sel_hi:[1,0]
	v_pk_mul_f32 v[130:131], v[94:95], v[160:161] op_sel_hi:[1,0]
	v_lshl_add_u64 v[176:177], v[176:177], 4, s[18:19]
	global_store_dwordx4 v[176:177], v[130:133], off
	v_or_b32_e32 v176, 48, v172
	v_ashrrev_i32_e32 v177, 31, v176
	v_pk_mul_f32 v[132:133], v[80:81], v[162:163] op_sel_hi:[1,0]
	v_pk_mul_f32 v[130:131], v[78:79], v[162:163] op_sel_hi:[1,0]
	v_lshl_add_u64 v[176:177], v[176:177], 4, s[18:19]
	global_store_dwordx4 v[176:177], v[130:133], off
	s_nop 1
	v_pk_mul_f32 v[132:133], v[64:65], v[164:165] op_sel_hi:[1,0]
	v_pk_mul_f32 v[130:131], v[62:63], v[164:165] op_sel_hi:[1,0]
	global_store_dwordx4 v[174:175], v[130:133], off offset:2048
	s_nop 1
	v_pk_mul_f32 v[132:133], v[48:49], v[166:167] op_sel_hi:[1,0]
	v_pk_mul_f32 v[130:131], v[46:47], v[166:167] op_sel_hi:[1,0]
	global_store_dwordx4 v[174:175], v[130:133], off offset:2304
	s_nop 1
	v_pk_mul_f32 v[132:133], v[32:33], v[168:169] op_sel_hi:[1,0]
	v_pk_mul_f32 v[130:131], v[30:31], v[168:169] op_sel_hi:[1,0]
	global_store_dwordx4 v[174:175], v[130:133], off offset:2560
	s_nop 1
	v_pk_mul_f32 v[132:133], v[16:17], v[170:171] op_sel_hi:[1,0]
	v_pk_mul_f32 v[130:131], v[14:15], v[170:171] op_sel_hi:[1,0]
	global_store_dwordx4 v[174:175], v[130:133], off offset:2816

.LBB0_879:
	s_mov_b32 s15, s77
	s_andn2_b64 vcc, exec, s[4:5]
	v_lshl_add_u32 v174, s35, 8, v147
	v_ashrrev_i32_e32 v175, 31, v174
	v_lshlrev_b64 v[130:131], 6, v[174:175]
	v_lshl_add_u64 v[130:131], v[140:141], 0, v[130:131]
	global_load_dwordx4 v[178:181], v[130:131], off
	global_load_dwordx4 v[182:185], v[130:131], off offset:1024
	global_load_dwordx4 v[192:195], v[130:131], off offset:2048
	global_load_dwordx4 v[196:199], v[130:131], off offset:3072
	s_mov_b64 s[100:101], 0x2000
	v_lshl_add_u64 v[246:247], v[130:131], 0, s[100:101]
	global_load_dwordx4 v[204:207], v[246:247], off
	global_load_dwordx4 v[208:211], v[246:247], off offset:1024
	global_load_dwordx4 v[216:219], v[246:247], off offset:2048
	global_load_dwordx4 v[224:227], v[246:247], off offset:3072
	v_or_b32_e32 v172, 16, v174
	v_ashrrev_i32_e32 v173, 31, v172
	v_or_b32_e32 v170, 32, v174
	v_ashrrev_i32_e32 v171, 31, v170
	v_or_b32_e32 v168, 48, v174
	v_ashrrev_i32_e32 v169, 31, v168
	v_add_u32_e32 v162, 0x80, v174
	v_ashrrev_i32_e32 v163, 31, v162
	v_add_u32_e32 v158, 0x90, v174
	v_ashrrev_i32_e32 v159, 31, v158
	v_add_u32_e32 v154, 0xa0, v174
	v_ashrrev_i32_e32 v155, 31, v154
	s_waitcnt vmcnt(7)
	v_mov_b64_e32 v[130:131], v[178:179]
	v_mov_b64_e32 v[132:133], v[180:181]
	v_mov_b32_e32 v150, v131
	v_mov_b32_e32 v151, v132
	v_mov_b32_e32 v131, v133
	v_pk_add_f32 v[130:131], v[150:151], v[130:131]
	s_nop 0
	v_add_f32_e32 v130, v130, v131
	ds_swizzle_b32 v131, v130 offset:swizzle(SWAP,16)
	s_waitcnt lgkmcnt(0)
	v_add_f32_e32 v130, v130, v131
	v_mov_b32_e32 v131, v130
	s_nop 1
	v_permlane32_swap_b32_e32 v130, v131
	v_add_f32_e32 v130, v130, v131
	v_fmamk_f32 v130, v130, 0x3a800000, v241
	v_rsq_f32_e32 v166, v130
	s_nop 1
	v_pk_mul_f32 v[128:129], v[128:129], v[166:167] op_sel_hi:[1,0]
	v_pk_mul_f32 v[126:127], v[126:127], v[166:167] op_sel_hi:[1,0]
	v_pk_mul_f32 v[122:123], v[122:123], v[166:167] op_sel_hi:[1,0]
	v_pk_mul_f32 v[124:125], v[124:125], v[166:167] op_sel_hi:[1,0]
	v_max_f32_e32 v126, 0, v126
	v_max_f32_e32 v122, 0, v122
	v_max_f32_e32 v127, 0, v127
	v_max_f32_e32 v123, 0, v123
	v_max_f32_e32 v128, 0, v128
	v_max_f32_e32 v129, 0, v129
	v_pk_mul_f32 v[126:127], v[126:127], v[126:127]
	v_pk_mul_f32 v[122:123], v[122:123], v[122:123]
	v_max_f32_e32 v124, 0, v124
	v_max_f32_e32 v125, 0, v125
	v_pk_mul_f32 v[128:129], v[128:129], v[128:129]
	v_pk_mul_f32 v[114:115], v[114:115], v[166:167] op_sel_hi:[1,0]
	v_pk_mul_f32 v[120:121], v[120:121], v[166:167] op_sel_hi:[1,0]
	v_pk_mul_f32 v[118:119], v[118:119], v[166:167] op_sel_hi:[1,0]
	v_pk_mul_f32 v[116:117], v[116:117], v[166:167] op_sel_hi:[1,0]
	v_max_f32_e32 v114, 0, v114
	v_max_f32_e32 v115, 0, v115
	v_max_f32_e32 v118, 0, v118
	v_max_f32_e32 v119, 0, v119
	v_max_f32_e32 v116, 0, v116
	v_max_f32_e32 v117, 0, v117
	v_pk_mul_f32 v[118:119], v[118:119], v[118:119]
	s_waitcnt vmcnt(6)
	v_mov_b64_e32 v[130:131], v[182:183]
	v_mov_b64_e32 v[132:133], v[184:185]
	v_mov_b32_e32 v150, v131
	v_mov_b32_e32 v151, v132
	v_mov_b32_e32 v131, v133
	v_pk_add_f32 v[130:131], v[150:151], v[130:131]
	s_nop 0
	v_add_f32_e32 v130, v130, v131
	ds_swizzle_b32 v131, v130 offset:swizzle(SWAP,16)
	s_waitcnt lgkmcnt(0)
	v_add_f32_e32 v130, v130, v131
	v_mov_b32_e32 v131, v130
	s_nop 1
	v_permlane32_swap_b32_e32 v130, v131
	v_add_f32_e32 v130, v130, v131
	v_fmamk_f32 v130, v130, 0x3a800000, v241
	v_rsq_f32_e32 v164, v130
	s_nop 1
	v_pk_mul_f32 v[110:111], v[110:111], v[164:165] op_sel_hi:[1,0]
	v_pk_mul_f32 v[106:107], v[106:107], v[164:165] op_sel_hi:[1,0]
	v_pk_mul_f32 v[112:113], v[112:113], v[164:165] op_sel_hi:[1,0]
	v_pk_mul_f32 v[108:109], v[108:109], v[164:165] op_sel_hi:[1,0]
	v_max_f32_e32 v110, 0, v110
	v_max_f32_e32 v106, 0, v106
	v_max_f32_e32 v111, 0, v111
	v_max_f32_e32 v107, 0, v107
	v_pk_mul_f32 v[110:111], v[110:111], v[110:111]
	v_max_f32_e32 v108, 0, v108
	v_max_f32_e32 v109, 0, v109
	v_pk_mul_f32 v[98:99], v[98:99], v[164:165] op_sel_hi:[1,0]
	v_pk_mul_f32 v[104:105], v[104:105], v[164:165] op_sel_hi:[1,0]
	v_pk_mul_f32 v[102:103], v[102:103], v[164:165] op_sel_hi:[1,0]
	v_pk_mul_f32 v[100:101], v[100:101], v[164:165] op_sel_hi:[1,0]
	v_max_f32_e32 v98, 0, v98
	v_max_f32_e32 v99, 0, v99
	v_max_f32_e32 v102, 0, v102
	v_max_f32_e32 v103, 0, v103
	v_max_f32_e32 v100, 0, v100
	v_max_f32_e32 v101, 0, v101
	v_pk_mul_f32 v[102:103], v[102:103], v[102:103]
	s_waitcnt vmcnt(5)
	v_mov_b64_e32 v[130:131], v[192:193]
	v_mov_b64_e32 v[132:133], v[194:195]
	v_mov_b32_e32 v150, v131
	v_mov_b32_e32 v151, v132
	v_mov_b32_e32 v131, v133
	v_pk_add_f32 v[130:131], v[150:151], v[130:131]
	s_nop 0
	v_add_f32_e32 v130, v130, v131
	ds_swizzle_b32 v131, v130 offset:swizzle(SWAP,16)
	s_waitcnt lgkmcnt(0)
	v_add_f32_e32 v130, v130, v131
	v_mov_b32_e32 v131, v130
	s_nop 1
	v_permlane32_swap_b32_e32 v130, v131
	v_add_f32_e32 v130, v130, v131
	v_fmamk_f32 v130, v130, 0x3a800000, v241
	v_rsq_f32_e32 v160, v130
	s_nop 1
	v_pk_mul_f32 v[94:95], v[94:95], v[160:161] op_sel_hi:[1,0]
	v_pk_mul_f32 v[90:91], v[90:91], v[160:161] op_sel_hi:[1,0]
	v_pk_mul_f32 v[96:97], v[96:97], v[160:161] op_sel_hi:[1,0]
	v_pk_mul_f32 v[92:93], v[92:93], v[160:161] op_sel_hi:[1,0]
	v_max_f32_e32 v94, 0, v94
	v_max_f32_e32 v90, 0, v90
	v_max_f32_e32 v95, 0, v95
	v_max_f32_e32 v91, 0, v91
	v_pk_mul_f32 v[94:95], v[94:95], v[94:95]
	v_max_f32_e32 v92, 0, v92
	v_max_f32_e32 v93, 0, v93
	v_pk_mul_f32 v[82:83], v[82:83], v[160:161] op_sel_hi:[1,0]
	v_pk_mul_f32 v[88:89], v[88:89], v[160:161] op_sel_hi:[1,0]
	v_pk_mul_f32 v[86:87], v[86:87], v[160:161] op_sel_hi:[1,0]
	v_pk_mul_f32 v[84:85], v[84:85], v[160:161] op_sel_hi:[1,0]
	v_max_f32_e32 v82, 0, v82
	v_max_f32_e32 v83, 0, v83
	v_max_f32_e32 v86, 0, v86
	v_max_f32_e32 v87, 0, v87
	v_max_f32_e32 v84, 0, v84
	v_max_f32_e32 v85, 0, v85
	v_pk_mul_f32 v[86:87], v[86:87], v[86:87]
	s_waitcnt vmcnt(4)
	v_mov_b64_e32 v[130:131], v[196:197]
	v_mov_b64_e32 v[132:133], v[198:199]
	v_mov_b32_e32 v150, v131
	v_mov_b32_e32 v151, v132
	v_mov_b32_e32 v131, v133
	v_pk_add_f32 v[130:131], v[150:151], v[130:131]
	s_nop 0
	v_add_f32_e32 v130, v130, v131
	ds_swizzle_b32 v131, v130 offset:swizzle(SWAP,16)
	s_waitcnt lgkmcnt(0)
	v_add_f32_e32 v130, v130, v131
	v_mov_b32_e32 v131, v130
	s_nop 1
	v_permlane32_swap_b32_e32 v130, v131
	v_add_f32_e32 v130, v130, v131
	v_fmamk_f32 v130, v130, 0x3a800000, v241
	v_rsq_f32_e32 v156, v130
	s_nop 1
	v_pk_mul_f32 v[78:79], v[78:79], v[156:157] op_sel_hi:[1,0]
	v_pk_mul_f32 v[74:75], v[74:75], v[156:157] op_sel_hi:[1,0]
	v_pk_mul_f32 v[80:81], v[80:81], v[156:157] op_sel_hi:[1,0]
	v_pk_mul_f32 v[76:77], v[76:77], v[156:157] op_sel_hi:[1,0]
	v_max_f32_e32 v78, 0, v78
	v_max_f32_e32 v74, 0, v74
	v_max_f32_e32 v79, 0, v79
	v_max_f32_e32 v75, 0, v75
	v_pk_mul_f32 v[78:79], v[78:79], v[78:79]
	v_max_f32_e32 v76, 0, v76
	v_max_f32_e32 v77, 0, v77
	v_pk_mul_f32 v[66:67], v[66:67], v[156:157] op_sel_hi:[1,0]
	v_pk_mul_f32 v[72:73], v[72:73], v[156:157] op_sel_hi:[1,0]
	v_pk_mul_f32 v[70:71], v[70:71], v[156:157] op_sel_hi:[1,0]
	v_pk_mul_f32 v[68:69], v[68:69], v[156:157] op_sel_hi:[1,0]
	v_max_f32_e32 v66, 0, v66
	v_max_f32_e32 v67, 0, v67
	v_max_f32_e32 v70, 0, v70
	v_max_f32_e32 v71, 0, v71
	v_max_f32_e32 v68, 0, v68
	v_max_f32_e32 v69, 0, v69
	v_pk_mul_f32 v[70:71], v[70:71], v[70:71]
	s_waitcnt vmcnt(3)
	v_mov_b64_e32 v[130:131], v[204:205]
	v_mov_b64_e32 v[132:133], v[206:207]
	v_mov_b32_e32 v150, v131
	v_mov_b32_e32 v151, v132
	v_mov_b32_e32 v131, v133
	v_pk_add_f32 v[130:131], v[150:151], v[130:131]
	s_nop 0
	v_add_f32_e32 v130, v130, v131
	ds_swizzle_b32 v131, v130 offset:swizzle(SWAP,16)
	s_waitcnt lgkmcnt(0)
	v_add_f32_e32 v130, v130, v131
	v_mov_b32_e32 v131, v130
	s_nop 1
	v_permlane32_swap_b32_e32 v130, v131
	v_add_f32_e32 v130, v130, v131
	v_fmamk_f32 v130, v130, 0x3a800000, v241
	v_rsq_f32_e32 v152, v130
	s_nop 1
	v_pk_mul_f32 v[62:63], v[62:63], v[152:153] op_sel_hi:[1,0]
	v_pk_mul_f32 v[58:59], v[58:59], v[152:153] op_sel_hi:[1,0]
	v_pk_mul_f32 v[64:65], v[64:65], v[152:153] op_sel_hi:[1,0]
	v_pk_mul_f32 v[60:61], v[60:61], v[152:153] op_sel_hi:[1,0]
	v_max_f32_e32 v62, 0, v62
	v_max_f32_e32 v58, 0, v58
	v_max_f32_e32 v63, 0, v63
	v_max_f32_e32 v59, 0, v59
	v_pk_mul_f32 v[62:63], v[62:63], v[62:63]
	v_max_f32_e32 v60, 0, v60
	v_max_f32_e32 v61, 0, v61
	v_pk_mul_f32 v[50:51], v[50:51], v[152:153] op_sel_hi:[1,0]
	v_pk_mul_f32 v[56:57], v[56:57], v[152:153] op_sel_hi:[1,0]
	v_pk_mul_f32 v[54:55], v[54:55], v[152:153] op_sel_hi:[1,0]
	v_pk_mul_f32 v[52:53], v[52:53], v[152:153] op_sel_hi:[1,0]
	v_max_f32_e32 v50, 0, v50
	v_max_f32_e32 v51, 0, v51
	v_max_f32_e32 v54, 0, v54
	v_max_f32_e32 v55, 0, v55
	v_max_f32_e32 v52, 0, v52
	v_max_f32_e32 v53, 0, v53
	v_pk_mul_f32 v[54:55], v[54:55], v[54:55]
	s_waitcnt vmcnt(2)
	v_mov_b64_e32 v[130:131], v[208:209]
	v_mov_b64_e32 v[132:133], v[210:211]
	v_mov_b32_e32 v150, v131
	v_mov_b32_e32 v151, v132
	v_mov_b32_e32 v131, v133
	v_pk_add_f32 v[130:131], v[150:151], v[130:131]
	s_nop 0
	v_add_f32_e32 v130, v130, v131
	ds_swizzle_b32 v131, v130 offset:swizzle(SWAP,16)
	s_waitcnt lgkmcnt(0)
	v_add_f32_e32 v130, v130, v131
	v_mov_b32_e32 v131, v130
	s_nop 1
	v_permlane32_swap_b32_e32 v130, v131
	v_add_f32_e32 v130, v130, v131
	v_fmamk_f32 v130, v130, 0x3a800000, v241
	v_rsq_f32_e32 v148, v130
	s_nop 1
	v_pk_mul_f32 v[46:47], v[46:47], v[148:149] op_sel_hi:[1,0]
	v_pk_mul_f32 v[42:43], v[42:43], v[148:149] op_sel_hi:[1,0]
	v_pk_mul_f32 v[48:49], v[48:49], v[148:149] op_sel_hi:[1,0]
	v_pk_mul_f32 v[44:45], v[44:45], v[148:149] op_sel_hi:[1,0]
	v_max_f32_e32 v46, 0, v46
	v_max_f32_e32 v42, 0, v42
	v_max_f32_e32 v47, 0, v47
	v_max_f32_e32 v43, 0, v43
	v_pk_mul_f32 v[46:47], v[46:47], v[46:47]
	v_max_f32_e32 v44, 0, v44
	v_max_f32_e32 v45, 0, v45
	v_pk_mul_f32 v[34:35], v[34:35], v[148:149] op_sel_hi:[1,0]
	v_pk_mul_f32 v[40:41], v[40:41], v[148:149] op_sel_hi:[1,0]
	v_pk_mul_f32 v[38:39], v[38:39], v[148:149] op_sel_hi:[1,0]
	v_pk_mul_f32 v[36:37], v[36:37], v[148:149] op_sel_hi:[1,0]
	v_max_f32_e32 v34, 0, v34
	v_max_f32_e32 v35, 0, v35
	v_max_f32_e32 v38, 0, v38
	v_max_f32_e32 v39, 0, v39
	v_max_f32_e32 v36, 0, v36
	v_max_f32_e32 v37, 0, v37
	v_pk_mul_f32 v[38:39], v[38:39], v[38:39]
	s_waitcnt vmcnt(1)
	v_mov_b64_e32 v[130:131], v[216:217]
	v_mov_b64_e32 v[132:133], v[218:219]
	v_mov_b32_e32 v150, v131
	v_mov_b32_e32 v151, v132
	v_mov_b32_e32 v131, v133
	v_pk_add_f32 v[130:131], v[150:151], v[130:131]
	v_add_u32_e32 v150, 0xb0, v174
	v_add_f32_e32 v130, v130, v131
	ds_swizzle_b32 v131, v130 offset:swizzle(SWAP,16)
	v_ashrrev_i32_e32 v151, 31, v150
	v_lshlrev_b64 v[174:175], 13, v[174:175]
	s_waitcnt lgkmcnt(0)
	v_add_f32_e32 v130, v130, v131
	v_mov_b32_e32 v131, v130
	s_nop 1
	v_permlane32_swap_b32_e32 v130, v131
	v_add_f32_e32 v130, v130, v131
	v_fmamk_f32 v130, v130, 0x3a800000, v241
	v_rsq_f32_e32 v146, v130
	s_nop 1
	v_pk_mul_f32 v[30:31], v[30:31], v[146:147] op_sel_hi:[1,0]
	v_pk_mul_f32 v[26:27], v[26:27], v[146:147] op_sel_hi:[1,0]
	v_pk_mul_f32 v[32:33], v[32:33], v[146:147] op_sel_hi:[1,0]
	v_pk_mul_f32 v[28:29], v[28:29], v[146:147] op_sel_hi:[1,0]
	v_max_f32_e32 v30, 0, v30
	v_max_f32_e32 v26, 0, v26
	v_max_f32_e32 v31, 0, v31
	v_max_f32_e32 v27, 0, v27
	v_pk_mul_f32 v[30:31], v[30:31], v[30:31]
	v_max_f32_e32 v28, 0, v28
	v_max_f32_e32 v29, 0, v29
	v_pk_mul_f32 v[18:19], v[18:19], v[146:147] op_sel_hi:[1,0]
	v_pk_mul_f32 v[24:25], v[24:25], v[146:147] op_sel_hi:[1,0]
	v_pk_mul_f32 v[22:23], v[22:23], v[146:147] op_sel_hi:[1,0]
	v_pk_mul_f32 v[20:21], v[20:21], v[146:147] op_sel_hi:[1,0]
	v_max_f32_e32 v18, 0, v18
	v_max_f32_e32 v19, 0, v19
	v_max_f32_e32 v22, 0, v22
	v_max_f32_e32 v23, 0, v23
	v_max_f32_e32 v20, 0, v20
	v_max_f32_e32 v21, 0, v21
	v_pk_mul_f32 v[22:23], v[22:23], v[22:23]
	s_waitcnt vmcnt(0)
	v_mov_b64_e32 v[130:131], v[224:225]
	v_mov_b64_e32 v[132:133], v[226:227]
	v_mov_b32_e32 v177, v132
	v_lshl_or_b32 v132, s34, 8, v153
	v_mov_b32_e32 v176, v131
	v_mov_b32_e32 v131, v133
	v_ashrrev_i32_e32 v133, 31, v132
	v_pk_add_f32 v[130:131], v[176:177], v[130:131]
	v_pk_mul_f32 v[176:177], v[124:125], v[124:125]
	v_cvt_pk_bf16_f32 v124, v126, v127
	v_cvt_pk_bf16_f32 v125, v128, v129
	v_cvt_pk_bf16_f32 v126, v122, v123
	v_lshl_add_u64 v[128:129], s[6:7], 0, v[174:175]
	v_lshlrev_b64 v[122:123], 1, v[132:133]
	v_cvt_pk_bf16_f32 v127, v176, v177
	v_lshl_add_u64 v[128:129], v[128:129], 0, v[122:123]
	global_store_dwordx4 v[128:129], v[124:127], off
	v_add_f32_e32 v130, v130, v131
	ds_swizzle_b32 v131, v130 offset:swizzle(SWAP,16)
	v_pk_mul_f32 v[124:125], v[114:115], v[114:115]
	v_max_f32_e32 v114, 0, v120
	v_max_f32_e32 v115, 0, v121
	v_pk_mul_f32 v[120:121], v[114:115], v[114:115]
	v_pk_mul_f32 v[126:127], v[116:117], v[116:117]
	v_cvt_pk_bf16_f32 v114, v118, v119
	v_cvt_pk_bf16_f32 v115, v120, v121
	v_cvt_pk_bf16_f32 v116, v124, v125
	v_cvt_pk_bf16_f32 v117, v126, v127
	global_store_dwordx4 v[128:129], v[114:117], off offset:256
	v_pk_mul_f32 v[118:119], v[108:109], v[108:109]
	s_waitcnt lgkmcnt(0)
	v_add_f32_e32 v130, v130, v131
	v_lshlrev_b64 v[114:115], 13, v[172:173]
	v_pk_mul_f32 v[116:117], v[106:107], v[106:107]
	v_max_f32_e32 v106, 0, v112
	v_max_f32_e32 v107, 0, v113
	v_pk_mul_f32 v[112:113], v[106:107], v[106:107]
	v_cvt_pk_bf16_f32 v106, v110, v111
	v_lshl_add_u64 v[110:111], s[6:7], 0, v[114:115]
	v_cvt_pk_bf16_f32 v107, v112, v113
	v_cvt_pk_bf16_f32 v108, v116, v117
	v_cvt_pk_bf16_f32 v109, v118, v119
	v_lshl_add_u64 v[110:111], v[110:111], 0, v[122:123]
	global_store_dwordx4 v[110:111], v[106:109], off
	v_mov_b32_e32 v131, v130
	s_nop 1
	v_permlane32_swap_b32_e32 v130, v131
	v_pk_mul_f32 v[106:107], v[98:99], v[98:99]
	v_max_f32_e32 v98, 0, v104
	v_max_f32_e32 v99, 0, v105
	v_pk_mul_f32 v[104:105], v[98:99], v[98:99]
	v_pk_mul_f32 v[108:109], v[100:101], v[100:101]
	v_cvt_pk_bf16_f32 v98, v102, v103
	v_cvt_pk_bf16_f32 v99, v104, v105
	v_cvt_pk_bf16_f32 v100, v106, v107
	v_cvt_pk_bf16_f32 v101, v108, v109
	global_store_dwordx4 v[110:111], v[98:101], off offset:256
	v_pk_mul_f32 v[102:103], v[92:93], v[92:93]
	v_add_f32_e32 v130, v130, v131
	v_lshlrev_b64 v[98:99], 13, v[170:171]
	v_pk_mul_f32 v[100:101], v[90:91], v[90:91]
	v_max_f32_e32 v90, 0, v96
	v_max_f32_e32 v91, 0, v97
	v_pk_mul_f32 v[96:97], v[90:91], v[90:91]
	v_cvt_pk_bf16_f32 v90, v94, v95
	v_lshl_add_u64 v[94:95], s[6:7], 0, v[98:99]
	v_cvt_pk_bf16_f32 v91, v96, v97
	v_cvt_pk_bf16_f32 v92, v100, v101
	v_cvt_pk_bf16_f32 v93, v102, v103
	v_lshl_add_u64 v[94:95], v[94:95], 0, v[122:123]
	global_store_dwordx4 v[94:95], v[90:93], off
	v_fmamk_f32 v130, v130, 0x3a800000, v241
	v_rsq_f32_e32 v130, v130
	v_pk_mul_f32 v[90:91], v[82:83], v[82:83]
	v_max_f32_e32 v82, 0, v88
	v_max_f32_e32 v83, 0, v89
	v_pk_mul_f32 v[88:89], v[82:83], v[82:83]
	v_pk_mul_f32 v[92:93], v[84:85], v[84:85]
	v_cvt_pk_bf16_f32 v82, v86, v87
	v_cvt_pk_bf16_f32 v83, v88, v89
	v_cvt_pk_bf16_f32 v84, v90, v91
	v_cvt_pk_bf16_f32 v85, v92, v93
	global_store_dwordx4 v[94:95], v[82:85], off offset:256
	v_pk_mul_f32 v[86:87], v[76:77], v[76:77]
	v_pk_mul_f32 v[14:15], v[14:15], v[130:131] op_sel_hi:[1,0]
	v_lshlrev_b64 v[82:83], 13, v[168:169]
	v_pk_mul_f32 v[84:85], v[74:75], v[74:75]
	v_max_f32_e32 v74, 0, v80
	v_max_f32_e32 v75, 0, v81
	v_pk_mul_f32 v[80:81], v[74:75], v[74:75]
	v_cvt_pk_bf16_f32 v74, v78, v79
	v_lshl_add_u64 v[78:79], s[6:7], 0, v[82:83]
	v_cvt_pk_bf16_f32 v75, v80, v81
	v_cvt_pk_bf16_f32 v76, v84, v85
	v_cvt_pk_bf16_f32 v77, v86, v87
	v_lshl_add_u64 v[78:79], v[78:79], 0, v[122:123]
	global_store_dwordx4 v[78:79], v[74:77], off
	v_pk_mul_f32 v[10:11], v[10:11], v[130:131] op_sel_hi:[1,0]
	v_pk_mul_f32 v[16:17], v[16:17], v[130:131] op_sel_hi:[1,0]
	v_pk_mul_f32 v[74:75], v[66:67], v[66:67]
	v_max_f32_e32 v66, 0, v72
	v_max_f32_e32 v67, 0, v73
	v_pk_mul_f32 v[72:73], v[66:67], v[66:67]
	v_pk_mul_f32 v[76:77], v[68:69], v[68:69]
	v_cvt_pk_bf16_f32 v66, v70, v71
	v_cvt_pk_bf16_f32 v67, v72, v73
	v_cvt_pk_bf16_f32 v68, v74, v75
	v_cvt_pk_bf16_f32 v69, v76, v77
	global_store_dwordx4 v[78:79], v[66:69], off offset:256
	v_pk_mul_f32 v[70:71], v[60:61], v[60:61]
	v_pk_mul_f32 v[12:13], v[12:13], v[130:131] op_sel_hi:[1,0]
	v_lshlrev_b64 v[66:67], 13, v[162:163]
	v_pk_mul_f32 v[68:69], v[58:59], v[58:59]
	v_max_f32_e32 v58, 0, v64
	v_max_f32_e32 v59, 0, v65
	v_pk_mul_f32 v[64:65], v[58:59], v[58:59]
	v_cvt_pk_bf16_f32 v58, v62, v63
	v_lshl_add_u64 v[62:63], s[6:7], 0, v[66:67]
	v_cvt_pk_bf16_f32 v59, v64, v65
	v_cvt_pk_bf16_f32 v60, v68, v69
	v_cvt_pk_bf16_f32 v61, v70, v71
	v_lshl_add_u64 v[62:63], v[62:63], 0, v[122:123]
	global_store_dwordx4 v[62:63], v[58:61], off
	v_max_f32_e32 v14, 0, v14
	v_max_f32_e32 v10, 0, v10
	v_pk_mul_f32 v[58:59], v[50:51], v[50:51]
	v_max_f32_e32 v50, 0, v56
	v_max_f32_e32 v51, 0, v57
	v_pk_mul_f32 v[56:57], v[50:51], v[50:51]
	v_pk_mul_f32 v[60:61], v[52:53], v[52:53]
	v_cvt_pk_bf16_f32 v50, v54, v55
	v_cvt_pk_bf16_f32 v51, v56, v57
	v_cvt_pk_bf16_f32 v52, v58, v59
	v_cvt_pk_bf16_f32 v53, v60, v61
	global_store_dwordx4 v[62:63], v[50:53], off offset:256
	v_pk_mul_f32 v[54:55], v[44:45], v[44:45]
	v_max_f32_e32 v15, 0, v15
	v_lshlrev_b64 v[50:51], 13, v[158:159]
	v_pk_mul_f32 v[52:53], v[42:43], v[42:43]
	v_max_f32_e32 v42, 0, v48
	v_max_f32_e32 v43, 0, v49
	v_pk_mul_f32 v[48:49], v[42:43], v[42:43]
	v_cvt_pk_bf16_f32 v42, v46, v47
	v_lshl_add_u64 v[46:47], s[6:7], 0, v[50:51]
	v_cvt_pk_bf16_f32 v43, v48, v49
	v_cvt_pk_bf16_f32 v44, v52, v53
	v_cvt_pk_bf16_f32 v45, v54, v55
	v_lshl_add_u64 v[46:47], v[46:47], 0, v[122:123]
	global_store_dwordx4 v[46:47], v[42:45], off
	v_max_f32_e32 v11, 0, v11
	v_pk_mul_f32 v[14:15], v[14:15], v[14:15]
	v_pk_mul_f32 v[42:43], v[34:35], v[34:35]
	v_max_f32_e32 v34, 0, v40
	v_max_f32_e32 v35, 0, v41
	v_pk_mul_f32 v[40:41], v[34:35], v[34:35]
	v_pk_mul_f32 v[44:45], v[36:37], v[36:37]
	v_cvt_pk_bf16_f32 v34, v38, v39
	v_cvt_pk_bf16_f32 v35, v40, v41
	v_cvt_pk_bf16_f32 v36, v42, v43
	v_cvt_pk_bf16_f32 v37, v44, v45
	global_store_dwordx4 v[46:47], v[34:37], off offset:256
	v_pk_mul_f32 v[38:39], v[28:29], v[28:29]
	v_max_f32_e32 v12, 0, v12
	v_lshlrev_b64 v[34:35], 13, v[154:155]
	v_pk_mul_f32 v[36:37], v[26:27], v[26:27]
	v_max_f32_e32 v26, 0, v32
	v_max_f32_e32 v27, 0, v33
	v_pk_mul_f32 v[32:33], v[26:27], v[26:27]
	v_cvt_pk_bf16_f32 v26, v30, v31
	v_lshl_add_u64 v[30:31], s[6:7], 0, v[34:35]
	v_cvt_pk_bf16_f32 v27, v32, v33
	v_cvt_pk_bf16_f32 v28, v36, v37
	v_cvt_pk_bf16_f32 v29, v38, v39
	v_lshl_add_u64 v[30:31], v[30:31], 0, v[122:123]
	global_store_dwordx4 v[30:31], v[26:29], off
	v_max_f32_e32 v13, 0, v13
	v_pk_mul_f32 v[2:3], v[2:3], v[130:131] op_sel_hi:[1,0]
	v_pk_mul_f32 v[26:27], v[18:19], v[18:19]
	v_max_f32_e32 v18, 0, v24
	v_max_f32_e32 v19, 0, v25
	v_pk_mul_f32 v[24:25], v[18:19], v[18:19]
	v_pk_mul_f32 v[28:29], v[20:21], v[20:21]
	v_cvt_pk_bf16_f32 v18, v22, v23
	v_cvt_pk_bf16_f32 v19, v24, v25
	v_cvt_pk_bf16_f32 v20, v26, v27
	v_cvt_pk_bf16_f32 v21, v28, v29
	global_store_dwordx4 v[30:31], v[18:21], off offset:256
	v_pk_mul_f32 v[22:23], v[12:13], v[12:13]
	v_pk_mul_f32 v[8:9], v[8:9], v[130:131] op_sel_hi:[1,0]
	v_lshlrev_b64 v[18:19], 13, v[150:151]
	v_pk_mul_f32 v[20:21], v[10:11], v[10:11]
	v_max_f32_e32 v10, 0, v16
	v_max_f32_e32 v11, 0, v17
	v_pk_mul_f32 v[16:17], v[10:11], v[10:11]
	v_cvt_pk_bf16_f32 v10, v14, v15
	v_lshl_add_u64 v[14:15], s[6:7], 0, v[18:19]
	v_cvt_pk_bf16_f32 v11, v16, v17
	v_cvt_pk_bf16_f32 v12, v20, v21
	v_cvt_pk_bf16_f32 v13, v22, v23
	v_lshl_add_u64 v[14:15], v[14:15], 0, v[122:123]
	v_pk_mul_f32 v[6:7], v[6:7], v[130:131] op_sel_hi:[1,0]
	v_pk_mul_f32 v[4:5], v[4:5], v[130:131] op_sel_hi:[1,0]
	v_max_f32_e32 v2, 0, v2
	v_max_f32_e32 v3, 0, v3
	global_store_dwordx4 v[14:15], v[10:13], off
	v_max_f32_e32 v6, 0, v6
	v_max_f32_e32 v7, 0, v7
	v_pk_mul_f32 v[10:11], v[2:3], v[2:3]
	v_max_f32_e32 v2, 0, v8
	v_max_f32_e32 v4, 0, v4
	v_max_f32_e32 v3, 0, v9
	v_max_f32_e32 v5, 0, v5
	v_pk_mul_f32 v[6:7], v[6:7], v[6:7]
	v_pk_mul_f32 v[8:9], v[2:3], v[2:3]
	v_pk_mul_f32 v[12:13], v[4:5], v[4:5]
	v_cvt_pk_bf16_f32 v2, v6, v7
	v_cvt_pk_bf16_f32 v3, v8, v9
	v_cvt_pk_bf16_f32 v4, v10, v11
	v_cvt_pk_bf16_f32 v5, v12, v13
	s_mov_b64 s[34:35], -1
	global_store_dwordx4 v[14:15], v[2:5], off offset:256
	s_cbranch_vccnz .LBB0_867
	s_andn2_b64 vcc, exec, s[0:1]
	s_cbranch_vccnz .LBB0_866
	s_barrier
	s_branch .LBB0_866
